# row phases: 64-lane sum of squares via DPP adds and v_permlane16/32_swap instead of six dependent ds_bpermute round trips
# baseline (speedup 1.0000x reference)
.LBB0_35:
	s_or_b64 exec, exec, s[12:13]
	v_mov_b32_e32 v3, v0
	v_lshl_add_u64 v[2:3], v[4:5], 0, v[2:3]
	global_load_dwordx4 v[18:21], v[2:3], off nt
	global_load_dwordx4 v[10:13], v[2:3], off offset:1024 nt
	global_load_dwordx4 v[6:9], v[2:3], off offset:2048 nt
	s_nop 0
	global_load_dwordx4 v[2:5], v[2:3], off offset:3072 nt
	v_ashrrev_i32_e32 v45, 12, v52
	s_waitcnt vmcnt(7)
	v_mov_b32_e32 v62, v31
	s_waitcnt vmcnt(6)
	v_mov_b32_e32 v63, v27
	s_waitcnt vmcnt(5)
	v_mov_b32_e32 v70, v23
	s_waitcnt vmcnt(4)
	v_mov_b32_e32 v71, v15
	v_mov_b32_e32 v52, v30
	v_mov_b32_e32 v53, v26
	v_mov_b32_e32 v68, v22
	v_mov_b32_e32 v69, v14
	v_add_u32_e32 v96, 1, v45
	v_pk_mul_f32 v[62:63], v[62:63], v[62:63]
	v_pk_mul_f32 v[70:71], v[70:71], v[70:71]
	v_mov_b32_e32 v64, v32
	v_mov_b32_e32 v65, v28
	v_mov_b32_e32 v72, v24
	v_mov_b32_e32 v73, v16
	v_cndmask_b32_e64 v45, v96, 0, s[0:1]
	v_pk_fma_f32 v[52:53], v[52:53], v[52:53], v[62:63]
	v_pk_fma_f32 v[62:63], v[68:69], v[68:69], v[70:71]
	v_mov_b32_e32 v74, v25
	v_mov_b32_e32 v75, v17
	v_pk_fma_f32 v[52:53], v[64:65], v[64:65], v[52:53]
	v_pk_fma_f32 v[62:63], v[72:73], v[72:73], v[62:63]
	v_mul_hi_i32_i24_e32 v65, 0x3000, v45
	v_mul_i32_i24_e32 v64, 0x3000, v45
	v_pk_fma_f32 v[70:71], v[74:75], v[74:75], v[62:63]
	v_lshl_add_u64 v[62:63], s[30:31], 0, v[64:65]
	s_mov_b64 s[40:41], 0x1000
	v_mov_b32_e32 v66, v33
	v_mov_b32_e32 v67, v29
	v_mov_b32_e32 v43, v0
	v_lshl_add_u64 v[72:73], v[62:63], 0, s[40:41]
	v_pk_fma_f32 v[52:53], v[66:67], v[66:67], v[52:53]
	v_lshl_add_u64 v[74:75], v[62:63], 0, v[42:43]
	v_lshl_add_u64 v[66:67], v[72:73], 0, v[42:43]
	global_load_dwordx4 v[58:61], v[36:37], off
	global_load_dwordx4 v[62:65], v[74:75], off
	s_nop 0
	global_load_dwordx4 v[66:69], v[66:67], off
	v_mov_b32_e32 v77, v52
	v_mov_b32_e32 v79, v70
	s_mov_b32 s0, 0x3a800000
	s_mov_b32 s12, 0x800000
	v_mov_b32_e32 v45, v0
	v_mov_b32_e32 v49, v0
	s_add_i32 s43, s43, s2
	s_mov_b32 s98, 0x800000
	s_cmpk_gt_i32 s43, 0x13ff
	s_waitcnt vmcnt(6)
	v_mov_b32_e32 v82, v19
	s_waitcnt vmcnt(5)
	v_mov_b32_e32 v83, v11
	v_mov_b32_e32 v80, v18
	v_mov_b32_e32 v81, v10
	s_waitcnt vmcnt(4)
	v_mov_b32_e32 v90, v7
	s_waitcnt vmcnt(3)
	v_mov_b32_e32 v91, v3
	v_pk_mul_f32 v[82:83], v[82:83], v[82:83]
	v_mov_b32_e32 v84, v20
	v_mov_b32_e32 v85, v12
	v_mov_b32_e32 v88, v6
	v_mov_b32_e32 v89, v2
	v_pk_mul_f32 v[90:91], v[90:91], v[90:91]
	v_pk_fma_f32 v[80:81], v[80:81], v[80:81], v[82:83]
	v_mov_b32_e32 v86, v21
	v_mov_b32_e32 v87, v13
	v_mov_b32_e32 v92, v8
	v_mov_b32_e32 v93, v4
	v_pk_fma_f32 v[82:83], v[88:89], v[88:89], v[90:91]
	v_pk_fma_f32 v[80:81], v[84:85], v[84:85], v[80:81]
	v_mov_b32_e32 v94, v9
	v_mov_b32_e32 v95, v5
	v_pk_fma_f32 v[82:83], v[92:93], v[92:93], v[82:83]
	v_pk_fma_f32 v[80:81], v[86:87], v[86:87], v[80:81]
	v_pk_fma_f32 v[82:83], v[94:95], v[94:95], v[82:83]
	v_mov_b32_e32 v76, v80
	v_mov_b32_e32 v52, v81
	v_mov_b32_e32 v78, v82
	v_pk_add_f32 v[52:53], v[76:77], v[52:53]
	v_mov_b32_e32 v70, v83
	v_pk_add_f32 v[52:53], v[52:53], v[78:79]
	v_lshlrev_b64 v[76:77], 11, v[40:41]
	v_pk_add_f32 v[52:53], v[52:53], v[70:71]
	v_lshl_add_u64 v[76:77], v[38:39], 0, v[76:77]
	v_add_u32_e32 v40, s42, v40
	s_nop 1
	v_add_f32_dpp v52, v52, v52 quad_perm:[1,0,3,2] row_mask:0xf bank_mask:0xf
	v_add_f32_dpp v53, v53, v53 quad_perm:[1,0,3,2] row_mask:0xf bank_mask:0xf
	s_waitcnt vmcnt(0)
	v_pk_add_f32 v[66:67], v[66:67], 1.0 op_sel_hi:[1,0]
	v_pk_add_f32 v[68:69], v[68:69], 1.0 op_sel_hi:[1,0]
	s_nop 1
	v_add_f32_dpp v52, v52, v52 quad_perm:[2,3,0,1] row_mask:0xf bank_mask:0xf
	v_add_f32_dpp v53, v53, v53 quad_perm:[2,3,0,1] row_mask:0xf bank_mask:0xf
	s_nop 1
	v_add_f32_dpp v52, v52, v52 row_half_mirror row_mask:0xf bank_mask:0xf
	v_add_f32_dpp v53, v53, v53 row_half_mirror row_mask:0xf bank_mask:0xf
	s_nop 1
	v_add_f32_dpp v52, v52, v52 row_mirror row_mask:0xf bank_mask:0xf
	v_add_f32_dpp v53, v53, v53 row_mirror row_mask:0xf bank_mask:0xf
	v_mov_b32_e32 v70, v52
	v_mov_b32_e32 v71, v53
	s_nop 1
	v_permlane16_swap_b32_e32 v52, v70
	v_permlane16_swap_b32_e32 v53, v71
	v_pk_add_f32 v[52:53], v[52:53], v[70:71]
	v_mov_b32_e32 v70, v52
	v_mov_b32_e32 v71, v53
	s_nop 1
	v_permlane32_swap_b32_e32 v52, v70
	v_permlane32_swap_b32_e32 v53, v71
	v_pk_add_f32 v[52:53], v[52:53], v[70:71]
	s_nop 0
	v_pk_fma_f32 v[52:53], v[52:53], s[0:1], v[148:149] op_sel_hi:[1,0,0]
	v_lshl_add_u64 v[70:71], v[72:73], 0, v[44:45]
	v_mul_f32_e32 v41, 0x4b800000, v53
	v_cmp_gt_f32_e64 s[0:1], s12, v53
	s_nop 1
	v_cndmask_b32_e64 v41, v53, v41, s[0:1]
	v_rsq_f32_e32 v41, v41
	s_nop 0
	v_mul_f32_e32 v47, 0x45800000, v41
	v_cndmask_b32_e64 v78, v41, v47, s[0:1]
	v_pk_mul_f32 v[30:31], v[30:31], v[78:79] op_sel_hi:[1,0]
	v_pk_mul_f32 v[32:33], v[32:33], v[78:79] op_sel_hi:[1,0]
	v_pk_mul_f32 v[30:31], v[58:59], v[30:31]
	v_pk_mul_f32 v[32:33], v[60:61], v[32:33]
	v_pk_fma_f32 v[30:31], v[66:67], v[30:31], v[62:63]
	v_pk_fma_f32 v[32:33], v[32:33], v[68:69], v[64:65]
	v_cvt_pk_bf16_f32 v30, v30, v31
	v_cvt_pk_bf16_f32 v31, v32, v33
	v_mov_b32_e32 v152, v30
	v_mov_b32_e32 v153, v31
	global_load_dwordx4 v[30:33], v[36:37], off offset:1024
	s_nop 0
	global_load_dwordx4 v[58:61], v[70:71], off
	global_load_dwordx4 v[62:65], v[74:75], off offset:1024
	v_pk_mul_f32 v[26:27], v[26:27], v[78:79] op_sel_hi:[1,0]
	v_pk_mul_f32 v[28:29], v[28:29], v[78:79] op_sel_hi:[1,0]
	v_mov_b32_e32 v47, v0
	v_lshl_add_u64 v[66:67], v[72:73], 0, v[46:47]
	v_pk_mul_f32 v[22:23], v[22:23], v[78:79] op_sel_hi:[1,0]
	v_pk_mul_f32 v[24:25], v[24:25], v[78:79] op_sel_hi:[1,0]
	v_pk_mul_f32 v[14:15], v[14:15], v[78:79] op_sel_hi:[1,0]
	v_pk_mul_f32 v[16:17], v[16:17], v[78:79] op_sel_hi:[1,0]
	v_cndmask_b32_e64 v41, v96, 0, vcc
	v_cmp_gt_f32_e32 vcc, s12, v52
	s_waitcnt vmcnt(2)
	v_pk_mul_f32 v[26:27], v[26:27], v[30:31]
	s_waitcnt vmcnt(1)
	v_pk_add_f32 v[30:31], v[58:59], 1.0 op_sel_hi:[1,0]
	v_pk_mul_f32 v[28:29], v[28:29], v[32:33]
	v_pk_add_f32 v[32:33], v[60:61], 1.0 op_sel_hi:[1,0]
	s_waitcnt vmcnt(0)
	v_pk_fma_f32 v[26:27], v[26:27], v[30:31], v[62:63]
	v_pk_fma_f32 v[28:29], v[28:29], v[32:33], v[64:65]
	v_cvt_pk_bf16_f32 v26, v26, v27
	v_cvt_pk_bf16_f32 v27, v28, v29
	v_mov_b32_e32 v154, v26
	v_mov_b32_e32 v155, v27
	global_load_dwordx4 v[26:29], v[36:37], off offset:2048
	s_nop 0
	global_load_dwordx4 v[30:33], v[66:67], off
	global_load_dwordx4 v[58:61], v[74:75], off offset:2048
	v_lshl_add_u64 v[62:63], v[72:73], 0, v[48:49]
	s_waitcnt vmcnt(2)
	v_pk_mul_f32 v[22:23], v[22:23], v[26:27]
	s_waitcnt vmcnt(1)
	v_pk_add_f32 v[26:27], v[30:31], 1.0 op_sel_hi:[1,0]
	v_pk_mul_f32 v[24:25], v[24:25], v[28:29]
	v_pk_add_f32 v[28:29], v[32:33], 1.0 op_sel_hi:[1,0]
	s_waitcnt vmcnt(0)
	v_pk_fma_f32 v[22:23], v[22:23], v[26:27], v[58:59]
	v_pk_fma_f32 v[24:25], v[24:25], v[28:29], v[60:61]
	v_cvt_pk_bf16_f32 v22, v22, v23
	v_cvt_pk_bf16_f32 v23, v24, v25
	v_mov_b32_e32 v156, v22
	v_mov_b32_e32 v157, v23
	global_load_dwordx4 v[22:25], v[36:37], off offset:3072
	s_nop 0
	global_load_dwordx4 v[26:29], v[62:63], off
	global_load_dwordx4 v[30:33], v[74:75], off offset:3072
	v_mul_hi_i32_i24_e32 v59, 0x3000, v41
	v_mul_i32_i24_e32 v58, 0x3000, v41
	v_lshl_add_u64 v[58:59], s[30:31], 0, v[58:59]
	v_lshl_add_u64 v[60:61], v[58:59], 0, s[40:41]
	v_lshl_add_u64 v[62:63], v[60:61], 0, v[42:43]
	s_waitcnt vmcnt(2)
	v_pk_mul_f32 v[14:15], v[14:15], v[22:23]
	s_waitcnt vmcnt(1)
	v_pk_add_f32 v[22:23], v[26:27], 1.0 op_sel_hi:[1,0]
	v_pk_mul_f32 v[16:17], v[16:17], v[24:25]
	v_pk_add_f32 v[24:25], v[28:29], 1.0 op_sel_hi:[1,0]
	s_waitcnt vmcnt(0)
	v_pk_fma_f32 v[14:15], v[14:15], v[22:23], v[30:31]
	v_pk_fma_f32 v[16:17], v[16:17], v[24:25], v[32:33]
	v_cvt_pk_bf16_f32 v14, v14, v15
	v_cvt_pk_bf16_f32 v15, v16, v17
	v_mov_b32_e32 v158, v14
	v_mov_b32_e32 v159, v15
	global_load_dwordx4 v[14:17], v[36:37], off
	s_nop 0
	global_load_dwordx4 v[22:25], v[62:63], off
	v_lshl_add_u64 v[30:31], v[58:59], 0, v[42:43]
	global_load_dwordx4 v[26:29], v[30:31], off
	v_mul_f32_e32 v32, 0x4b800000, v52
	v_cndmask_b32_e32 v32, v52, v32, vcc
	v_rsq_f32_e32 v41, v32
	v_lshlrev_b64 v[32:33], 11, v[50:51]
	v_lshl_add_u64 v[32:33], v[38:39], 0, v[32:33]
	v_lshl_add_u64 v[50:51], v[60:61], 0, v[44:45]
	v_mul_f32_e32 v43, 0x45800000, v41
	v_cndmask_b32_e32 v52, v41, v43, vcc
	v_pk_mul_f32 v[18:19], v[18:19], v[52:53] op_sel_hi:[1,0]
	v_pk_mul_f32 v[20:21], v[20:21], v[52:53] op_sel_hi:[1,0]
	v_pk_mul_f32 v[10:11], v[10:11], v[52:53] op_sel_hi:[1,0]
	v_pk_mul_f32 v[12:13], v[12:13], v[52:53] op_sel_hi:[1,0]
	v_pk_mul_f32 v[6:7], v[6:7], v[52:53] op_sel_hi:[1,0]
	v_pk_mul_f32 v[8:9], v[8:9], v[52:53] op_sel_hi:[1,0]
	v_pk_mul_f32 v[2:3], v[2:3], v[52:53] op_sel_hi:[1,0]
	v_pk_mul_f32 v[4:5], v[4:5], v[52:53] op_sel_hi:[1,0]
	s_waitcnt vmcnt(2)
	v_pk_mul_f32 v[14:15], v[14:15], v[18:19]
	s_waitcnt vmcnt(1)
	v_pk_add_f32 v[18:19], v[22:23], 1.0 op_sel_hi:[1,0]
	v_pk_mul_f32 v[16:17], v[16:17], v[20:21]
	v_pk_add_f32 v[20:21], v[24:25], 1.0 op_sel_hi:[1,0]
	s_waitcnt vmcnt(0)
	v_pk_fma_f32 v[14:15], v[18:19], v[14:15], v[26:27]
	v_pk_fma_f32 v[16:17], v[16:17], v[20:21], v[28:29]
	v_cvt_pk_bf16_f32 v14, v14, v15
	v_cvt_pk_bf16_f32 v15, v16, v17
	v_mov_b32_e32 v160, v14
	v_mov_b32_e32 v161, v15
	global_load_dwordx4 v[14:17], v[36:37], off offset:1024
	s_nop 0
	global_load_dwordx4 v[18:21], v[50:51], off
	global_load_dwordx4 v[22:25], v[30:31], off offset:1024
	v_lshl_add_u64 v[26:27], v[60:61], 0, v[46:47]
	s_waitcnt vmcnt(2)
	v_pk_mul_f32 v[10:11], v[10:11], v[14:15]
	s_waitcnt vmcnt(1)
	v_pk_add_f32 v[14:15], v[18:19], 1.0 op_sel_hi:[1,0]
	v_pk_mul_f32 v[12:13], v[12:13], v[16:17]
	v_pk_add_f32 v[16:17], v[20:21], 1.0 op_sel_hi:[1,0]
	s_waitcnt vmcnt(0)
	v_pk_fma_f32 v[10:11], v[10:11], v[14:15], v[22:23]
	v_pk_fma_f32 v[12:13], v[12:13], v[16:17], v[24:25]
	v_cvt_pk_bf16_f32 v10, v10, v11
	v_cvt_pk_bf16_f32 v11, v12, v13
	v_mov_b32_e32 v162, v10
	v_mov_b32_e32 v163, v11
	global_load_dwordx4 v[10:13], v[36:37], off offset:2048
	s_nop 0
	global_load_dwordx4 v[14:17], v[26:27], off
	global_load_dwordx4 v[18:21], v[30:31], off offset:2048
	v_lshl_add_u64 v[22:23], v[60:61], 0, v[48:49]
	s_waitcnt vmcnt(2)
	v_pk_mul_f32 v[6:7], v[6:7], v[10:11]
	s_waitcnt vmcnt(1)
	v_pk_add_f32 v[10:11], v[14:15], 1.0 op_sel_hi:[1,0]
	v_pk_mul_f32 v[8:9], v[8:9], v[12:13]
	v_pk_add_f32 v[12:13], v[16:17], 1.0 op_sel_hi:[1,0]
	s_waitcnt vmcnt(0)
	v_pk_fma_f32 v[6:7], v[6:7], v[10:11], v[18:19]
	v_pk_fma_f32 v[8:9], v[8:9], v[12:13], v[20:21]
	v_cvt_pk_bf16_f32 v6, v6, v7
	v_cvt_pk_bf16_f32 v7, v8, v9
	v_mov_b32_e32 v164, v6
	v_mov_b32_e32 v165, v7
	global_load_dwordx4 v[6:9], v[36:37], off offset:3072
	s_nop 0
	global_load_dwordx4 v[10:13], v[22:23], off
	global_load_dwordx4 v[14:17], v[30:31], off offset:3072
	s_waitcnt vmcnt(2)
	v_pk_mul_f32 v[2:3], v[2:3], v[6:7]
	s_waitcnt vmcnt(1)
	v_pk_add_f32 v[6:7], v[10:11], 1.0 op_sel_hi:[1,0]
	v_pk_mul_f32 v[4:5], v[4:5], v[8:9]
	v_pk_add_f32 v[8:9], v[12:13], 1.0 op_sel_hi:[1,0]
	s_waitcnt vmcnt(0)
	v_pk_fma_f32 v[2:3], v[2:3], v[6:7], v[14:15]
	v_pk_fma_f32 v[4:5], v[4:5], v[8:9], v[16:17]
	v_cvt_pk_bf16_f32 v2, v2, v3
	v_cvt_pk_bf16_f32 v3, v4, v5
	v_mov_b32_e32 v166, v2
	v_mov_b32_e32 v167, v3
	global_store_dwordx2 v[76:77], v[152:153], off
	global_store_dwordx2 v[76:77], v[154:155], off offset:512
	global_store_dwordx2 v[76:77], v[156:157], off offset:1024
	global_store_dwordx2 v[76:77], v[158:159], off offset:1536
	global_store_dwordx2 v[32:33], v[160:161], off
	global_store_dwordx2 v[32:33], v[162:163], off offset:512
	global_store_dwordx2 v[32:33], v[164:165], off offset:1024
	global_store_dwordx2 v[32:33], v[166:167], off offset:1536
	s_cbranch_scc1 .LBB0_44

.LBB0_182:
	s_waitcnt vmcnt(6)
	v_mov_b32_e32 v86, v26
	v_mov_b32_e32 v87, v30
	v_pk_mul_f32 v[86:87], v[86:87], v[86:87]
	v_mov_b32_e32 v88, v27
	v_mov_b32_e32 v89, v31
	v_pk_fma_f32 v[86:87], v[88:89], v[88:89], v[86:87]
	v_mov_b32_e32 v88, v28
	v_mov_b32_e32 v89, v32
	v_pk_fma_f32 v[86:87], v[88:89], v[88:89], v[86:87]
	v_mov_b32_e32 v88, v29
	v_mov_b32_e32 v89, v33
	v_pk_fma_f32 v[86:87], v[88:89], v[88:89], v[86:87]
	s_waitcnt vmcnt(4)
	v_mov_b32_e32 v88, v18
	v_mov_b32_e32 v89, v22
	v_pk_mul_f32 v[88:89], v[88:89], v[88:89]
	v_mov_b32_e32 v90, v19
	v_mov_b32_e32 v91, v23
	v_pk_fma_f32 v[88:89], v[90:91], v[90:91], v[88:89]
	v_mov_b32_e32 v90, v20
	v_mov_b32_e32 v91, v24
	v_pk_fma_f32 v[88:89], v[90:91], v[90:91], v[88:89]
	v_mov_b32_e32 v90, v21
	v_mov_b32_e32 v91, v25
	v_pk_fma_f32 v[88:89], v[90:91], v[90:91], v[88:89]
	v_add_f32_e32 v41, v86, v87
	v_add_f32_e32 v41, v89, v41
	v_readlane_b32 s0, v246, 41
	v_add_f32_e32 v41, v88, v41
	v_mov_b64_e32 v[88:89], s[30:31]
	v_add_u32_e32 v39, s0, v39
	v_mad_i64_i32 v[88:89], s[0:1], v39, s16, v[88:89]
	s_mov_b64 s[0:1], 0x1000
	s_nop 0
	v_lshl_add_u64 v[90:91], v[88:89], 0, s[0:1]
	v_mov_b32_e32 v79, v0
	v_lshl_add_u64 v[100:101], v[90:91], 0, v[78:79]
	v_lshl_add_u64 v[88:89], v[88:89], 0, v[78:79]
	global_load_dwordx4 v[92:95], v[48:49], off
	global_load_dwordx4 v[96:99], v[88:89], off
	s_nop 0
	global_load_dwordx4 v[100:103], v[100:101], off
	v_mov_b32_e32 v77, v0
	v_mov_b32_e32 v75, v0
	v_mov_b32_e32 v73, v0
	s_nop 1
	v_add_f32_dpp v41, v41, v41 quad_perm:[1,0,3,2] row_mask:0xf bank_mask:0xf
	s_nop 1
	s_nop 1
	v_add_f32_dpp v41, v41, v41 quad_perm:[2,3,0,1] row_mask:0xf bank_mask:0xf
	s_nop 1
	s_nop 1
	v_add_f32_dpp v41, v41, v41 row_half_mirror row_mask:0xf bank_mask:0xf
	s_nop 1
	s_nop 1
	v_add_f32_dpp v41, v41, v41 row_mirror row_mask:0xf bank_mask:0xf
	s_nop 1
	v_mov_b32_e32 v53, v41
	s_nop 1
	v_permlane16_swap_b32_e32 v41, v53
	v_add_f32_e32 v41, v41, v53
	s_nop 1
	v_mov_b32_e32 v43, v41
	s_nop 1
	v_permlane32_swap_b32_e32 v41, v43
	v_add_f32_e32 v41, v41, v43
	v_fmamk_f32 v41, v41, 0x3a800000, v148
	v_cmp_gt_f32_e32 vcc, s98, v41
	v_mul_f32_e32 v43, 0x4b800000, v41
	s_nop 0
	v_cndmask_b32_e32 v41, v41, v43, vcc
	v_rsq_f32_e32 v41, v41
	s_nop 0
	v_mul_f32_e32 v43, 0x45800000, v41
	v_cndmask_b32_e32 v86, v41, v43, vcc
	v_pk_mul_f32 v[30:31], v[30:31], v[86:87] op_sel_hi:[1,0]
	v_pk_mul_f32 v[26:27], v[26:27], v[86:87] op_sel_hi:[1,0]
	s_waitcnt vmcnt(2)
	v_pk_mul_f32 v[30:31], v[92:93], v[30:31]
	s_waitcnt vmcnt(0)
	v_pk_add_f32 v[92:93], v[100:101], 1.0 op_sel_hi:[1,0]
	v_pk_mul_f32 v[28:29], v[28:29], v[86:87] op_sel_hi:[1,0]
	v_pk_fma_f32 v[30:31], v[92:93], v[30:31], v[96:97]
	v_pk_mul_f32 v[22:23], v[22:23], v[86:87] op_sel_hi:[1,0]
	v_cvt_pk_bf16_f32 v92, v30, v31
	v_pk_mul_f32 v[30:31], v[32:33], v[86:87] op_sel_hi:[1,0]
	v_pk_add_f32 v[32:33], v[102:103], 1.0 op_sel_hi:[1,0]
	v_pk_mul_f32 v[30:31], v[94:95], v[30:31]
	v_pk_mul_f32 v[24:25], v[24:25], v[86:87] op_sel_hi:[1,0]
	v_pk_fma_f32 v[30:31], v[30:31], v[32:33], v[98:99]
	v_lshl_add_u64 v[32:33], v[90:91], 0, v[76:77]
	v_cvt_pk_bf16_f32 v93, v30, v31
	v_lshl_add_u64 v[30:31], v[84:85], 1, v[50:51]
	global_store_dwordx2 v[30:31], v[92:93], off
	global_load_dwordx4 v[92:95], v[48:49], off offset:1024
	s_nop 0
	global_load_dwordx4 v[96:99], v[88:89], off offset:1024
	global_load_dwordx4 v[100:103], v[32:33], off
	v_pk_mul_f32 v[18:19], v[18:19], v[86:87] op_sel_hi:[1,0]
	v_pk_mul_f32 v[20:21], v[20:21], v[86:87] op_sel_hi:[1,0]
	s_waitcnt vmcnt(2)
	v_pk_mul_f32 v[26:27], v[26:27], v[92:93]
	v_pk_mul_f32 v[28:29], v[28:29], v[94:95]
	s_waitcnt vmcnt(0)
	v_pk_add_f32 v[32:33], v[100:101], 1.0 op_sel_hi:[1,0]
	s_nop 0
	v_pk_fma_f32 v[26:27], v[26:27], v[32:33], v[96:97]
	v_pk_add_f32 v[32:33], v[102:103], 1.0 op_sel_hi:[1,0]
	v_cvt_pk_bf16_f32 v26, v26, v27
	v_pk_fma_f32 v[28:29], v[28:29], v[32:33], v[98:99]
	v_lshl_add_u64 v[32:33], v[90:91], 0, v[74:75]
	v_cvt_pk_bf16_f32 v27, v28, v29
	global_store_dwordx2 v[30:31], v[26:27], off offset:512
	global_load_dwordx4 v[26:29], v[48:49], off offset:2048
	s_nop 0
	global_load_dwordx4 v[92:95], v[88:89], off offset:2048
	global_load_dwordx4 v[96:99], v[32:33], off
	v_lshl_add_u64 v[32:33], v[90:91], 0, v[72:73]
	s_waitcnt vmcnt(2)
	v_pk_mul_f32 v[22:23], v[22:23], v[26:27]
	v_pk_mul_f32 v[24:25], v[24:25], v[28:29]
	s_waitcnt vmcnt(0)
	v_pk_add_f32 v[26:27], v[96:97], 1.0 op_sel_hi:[1,0]
	s_nop 0
	v_pk_fma_f32 v[22:23], v[22:23], v[26:27], v[92:93]
	v_pk_add_f32 v[26:27], v[98:99], 1.0 op_sel_hi:[1,0]
	v_cvt_pk_bf16_f32 v22, v22, v23
	v_pk_fma_f32 v[24:25], v[24:25], v[26:27], v[94:95]
	s_nop 0
	v_cvt_pk_bf16_f32 v23, v24, v25
	global_store_dwordx2 v[30:31], v[22:23], off offset:1024
	global_load_dwordx4 v[22:25], v[48:49], off offset:3072
	s_nop 0
	global_load_dwordx4 v[26:29], v[88:89], off offset:3072
	s_nop 0
	global_load_dwordx4 v[88:91], v[32:33], off
	s_waitcnt vmcnt(2)
	v_pk_mul_f32 v[18:19], v[18:19], v[22:23]
	v_pk_mul_f32 v[20:21], v[20:21], v[24:25]
	s_waitcnt vmcnt(0)
	v_pk_add_f32 v[22:23], v[88:89], 1.0 op_sel_hi:[1,0]
	s_nop 0
	v_pk_fma_f32 v[18:19], v[18:19], v[22:23], v[26:27]
	v_pk_add_f32 v[22:23], v[90:91], 1.0 op_sel_hi:[1,0]
	v_cvt_pk_bf16_f32 v18, v18, v19
	v_pk_fma_f32 v[20:21], v[20:21], v[22:23], v[28:29]
	s_nop 0
	v_cvt_pk_bf16_f32 v19, v20, v21
	global_store_dwordx2 v[30:31], v[18:19], off offset:1536
	s_and_b64 vcc, exec, s[40:41]
	v_cndmask_b32_e64 v19, v37, 0, s[42:43]
	s_cbranch_vccnz .LBB0_181

.LBB0_184:
	s_waitcnt vmcnt(2)
	v_mov_b32_e32 v20, v10
	v_mov_b32_e32 v21, v14
	v_pk_mul_f32 v[20:21], v[20:21], v[20:21]
	v_mov_b32_e32 v22, v11
	v_mov_b32_e32 v23, v15
	v_pk_fma_f32 v[20:21], v[22:23], v[22:23], v[20:21]
	v_mov_b32_e32 v22, v12
	v_mov_b32_e32 v23, v16
	v_pk_fma_f32 v[20:21], v[22:23], v[22:23], v[20:21]
	v_mov_b32_e32 v22, v13
	v_mov_b32_e32 v23, v17
	v_pk_fma_f32 v[20:21], v[22:23], v[22:23], v[20:21]
	s_waitcnt vmcnt(0)
	v_mov_b32_e32 v22, v2
	v_mov_b32_e32 v23, v6
	v_pk_mul_f32 v[22:23], v[22:23], v[22:23]
	v_mov_b32_e32 v24, v3
	v_mov_b32_e32 v25, v7
	v_pk_fma_f32 v[22:23], v[24:25], v[24:25], v[22:23]
	v_mov_b32_e32 v24, v4
	v_mov_b32_e32 v25, v8
	v_add_f32_e32 v18, v20, v21
	v_pk_fma_f32 v[22:23], v[24:25], v[24:25], v[22:23]
	v_mov_b32_e32 v24, v5
	v_mov_b32_e32 v25, v9
	v_pk_fma_f32 v[22:23], v[24:25], v[24:25], v[22:23]
	v_add_f32_e32 v18, v23, v18
	v_add_f32_e32 v18, v22, v18
	v_readlane_b32 s0, v246, 41
	v_mov_b32_e32 v79, v0
	v_mov_b32_e32 v77, v0
	v_add_u32_e32 v19, s0, v19
	s_nop 1
	v_add_f32_dpp v18, v18, v18 quad_perm:[1,0,3,2] row_mask:0xf bank_mask:0xf
	v_mov_b32_e32 v75, v0
	v_mov_b32_e32 v73, v0
	s_nop 1
	v_add_f32_dpp v18, v18, v18 quad_perm:[2,3,0,1] row_mask:0xf bank_mask:0xf
	s_nop 1
	s_nop 1
	v_add_f32_dpp v18, v18, v18 row_half_mirror row_mask:0xf bank_mask:0xf
	s_nop 1
	s_nop 1
	v_add_f32_dpp v18, v18, v18 row_mirror row_mask:0xf bank_mask:0xf
	s_nop 1
	v_mov_b32_e32 v21, v18
	s_nop 1
	v_permlane16_swap_b32_e32 v18, v21
	v_add_f32_e32 v18, v18, v21
	s_nop 1
	v_mov_b32_e32 v20, v18
	s_nop 1
	v_permlane32_swap_b32_e32 v18, v20
	v_add_f32_e32 v18, v18, v20
	v_fmamk_f32 v18, v18, 0x3a800000, v148
	v_cmp_gt_f32_e32 vcc, s98, v18
	v_mul_f32_e32 v20, 0x4b800000, v18
	s_nop 0
	v_cndmask_b32_e32 v18, v18, v20, vcc
	v_rsq_f32_e32 v18, v18
	s_nop 0
	v_mul_f32_e32 v20, 0x45800000, v18
	v_cndmask_b32_e32 v18, v18, v20, vcc
	v_mov_b64_e32 v[20:21], s[30:31]
	v_mad_i64_i32 v[20:21], s[0:1], v19, s16, v[20:21]
	s_mov_b64 s[0:1], 0x1000
	s_nop 0
	v_lshl_add_u64 v[22:23], v[20:21], 0, s[0:1]
	v_lshl_add_u64 v[20:21], v[20:21], 0, v[78:79]
	v_lshl_add_u64 v[32:33], v[22:23], 0, v[78:79]
	global_load_dwordx4 v[24:27], v[48:49], off
	global_load_dwordx4 v[28:31], v[20:21], off
	global_load_dwordx4 v[78:81], v[32:33], off
	v_pk_mul_f32 v[14:15], v[14:15], v[18:19] op_sel_hi:[1,0]
	v_pk_mul_f32 v[10:11], v[10:11], v[18:19] op_sel_hi:[1,0]
	v_pk_mul_f32 v[12:13], v[12:13], v[18:19] op_sel_hi:[1,0]
	v_pk_mul_f32 v[6:7], v[6:7], v[18:19] op_sel_hi:[1,0]
	v_pk_mul_f32 v[8:9], v[8:9], v[18:19] op_sel_hi:[1,0]
	v_pk_mul_f32 v[2:3], v[2:3], v[18:19] op_sel_hi:[1,0]
	v_pk_mul_f32 v[4:5], v[4:5], v[18:19] op_sel_hi:[1,0]
	s_waitcnt vmcnt(2)
	v_pk_mul_f32 v[14:15], v[24:25], v[14:15]
	s_waitcnt vmcnt(0)
	v_pk_add_f32 v[24:25], v[78:79], 1.0 op_sel_hi:[1,0]
	s_nop 0
	v_pk_fma_f32 v[14:15], v[24:25], v[14:15], v[28:29]
	s_nop 0
	v_cvt_pk_bf16_f32 v24, v14, v15
	v_pk_mul_f32 v[14:15], v[16:17], v[18:19] op_sel_hi:[1,0]
	v_pk_add_f32 v[16:17], v[80:81], 1.0 op_sel_hi:[1,0]
	v_pk_mul_f32 v[14:15], v[26:27], v[14:15]
	s_nop 0
	v_pk_fma_f32 v[14:15], v[14:15], v[16:17], v[30:31]
	v_lshl_add_u64 v[16:17], v[22:23], 0, v[76:77]
	v_cvt_pk_bf16_f32 v25, v14, v15
	v_lshl_add_u64 v[14:15], v[70:71], 1, v[50:51]
	global_store_dwordx2 v[14:15], v[24:25], off
	global_load_dwordx4 v[24:27], v[48:49], off offset:1024
	s_nop 0
	global_load_dwordx4 v[28:31], v[20:21], off offset:1024
	global_load_dwordx4 v[76:79], v[16:17], off
	s_waitcnt vmcnt(2)
	v_pk_mul_f32 v[10:11], v[10:11], v[24:25]
	v_pk_mul_f32 v[12:13], v[12:13], v[26:27]
	s_waitcnt vmcnt(0)
	v_pk_add_f32 v[16:17], v[76:77], 1.0 op_sel_hi:[1,0]
	s_nop 0
	v_pk_fma_f32 v[10:11], v[10:11], v[16:17], v[28:29]
	v_pk_add_f32 v[16:17], v[78:79], 1.0 op_sel_hi:[1,0]
	v_cvt_pk_bf16_f32 v10, v10, v11
	v_pk_fma_f32 v[12:13], v[12:13], v[16:17], v[30:31]
	v_lshl_add_u64 v[16:17], v[22:23], 0, v[74:75]
	v_cvt_pk_bf16_f32 v11, v12, v13
	global_store_dwordx2 v[14:15], v[10:11], off offset:512
	global_load_dwordx4 v[10:13], v[48:49], off offset:2048
	s_nop 0
	global_load_dwordx4 v[24:27], v[20:21], off offset:2048
	global_load_dwordx4 v[28:31], v[16:17], off
	v_lshl_add_u64 v[16:17], v[22:23], 0, v[72:73]
	s_waitcnt vmcnt(2)
	v_pk_mul_f32 v[6:7], v[6:7], v[10:11]
	v_pk_mul_f32 v[8:9], v[8:9], v[12:13]
	s_waitcnt vmcnt(0)
	v_pk_add_f32 v[10:11], v[28:29], 1.0 op_sel_hi:[1,0]
	s_nop 0
	v_pk_fma_f32 v[6:7], v[6:7], v[10:11], v[24:25]
	v_pk_add_f32 v[10:11], v[30:31], 1.0 op_sel_hi:[1,0]
	v_cvt_pk_bf16_f32 v6, v6, v7
	v_pk_fma_f32 v[8:9], v[8:9], v[10:11], v[26:27]
	s_nop 0
	v_cvt_pk_bf16_f32 v7, v8, v9
	global_store_dwordx2 v[14:15], v[6:7], off offset:1024
	global_load_dwordx4 v[6:9], v[48:49], off offset:3072
	s_nop 0
	global_load_dwordx4 v[10:13], v[20:21], off offset:3072
	s_nop 0
	global_load_dwordx4 v[20:23], v[16:17], off
	s_waitcnt vmcnt(2)
	v_pk_mul_f32 v[2:3], v[2:3], v[6:7]
	v_pk_mul_f32 v[4:5], v[4:5], v[8:9]
	s_waitcnt vmcnt(0)
	v_pk_add_f32 v[6:7], v[20:21], 1.0 op_sel_hi:[1,0]
	s_nop 0
	v_pk_fma_f32 v[2:3], v[2:3], v[6:7], v[10:11]
	v_pk_add_f32 v[6:7], v[22:23], 1.0 op_sel_hi:[1,0]
	v_cvt_pk_bf16_f32 v2, v2, v3
	v_pk_fma_f32 v[4:5], v[4:5], v[6:7], v[12:13]
	s_nop 0
	v_cvt_pk_bf16_f32 v3, v4, v5
	global_store_dwordx2 v[14:15], v[2:3], off offset:1536
	s_branch .LBB0_164
